# mixer-B dilated-window attention hand-written: six key tiles resident in LDS, two barriers per unit, exact softmax over the 3 band tiles
# speedup vs baseline: 1.0031x; 1.0031x over previous
.LBB0_308:
	s_add_i32 s3, s74, 0x5ff
	s_ashr_i32 s4, s3, 31
	s_abs_i32 s3, s3
	s_mul_i32 s1, s3, s1
	s_mul_hi_u32 s0, s3, s0
	s_add_i32 s0, s0, s1
	s_mul_i32 s1, s0, s16
	s_sub_i32 s1, s3, s1
	s_xor_b32 s4, s4, s17
	s_add_i32 s3, s0, 1
	s_sub_i32 s5, s1, s16
	s_cmp_ge_u32 s1, s16
	s_cselect_b32 s0, s3, s0
	s_cselect_b32 s1, s5, s1
	s_add_i32 s3, s0, 1
	s_cmp_ge_u32 s1, s16
	s_cselect_b32 s0, s3, s0
	s_xor_b32 s0, s0, s4
	s_sub_i32 s3, s0, s4
	s_cmp_lt_i32 s3, 1
	s_cbranch_scc1 .LBB0_392
	v_and_b32_e32 v1, 63, v0
	v_and_b32_e32 v180, 31, v0
	v_bfe_u32 v181, v0, 5, 1
	v_readfirstlane_b32 s31, v0
	s_nop 3
	s_lshr_b32 s31, s31, 6
	s_lshr_b32 s29, s31, 1
	s_mul_i32 s30, s29, 0x4800
	v_and_b32_e32 v189, 0x13, v180
	v_and_b32_e32 v190, 4, v180
	v_and_b32_e32 v191, 8, v180
	v_lshlrev_b32_e32 v190, 1, v190
	v_lshrrev_b32_e32 v191, 1, v191
	v_or3_b32 v189, v189, v190, v191
	v_mul_u32_u24_e32 v183, 0x90, v189
	v_lshl_add_u32 v183, v181, 4, v183
	v_add_u32_e32 v183, s30, v183
	v_bfe_u32 v189, v0, 2, 2
	v_lshl_add_u32 v189, v181, 3, v189
	v_mul_u32_u24_e32 v184, 0x90, v189
	v_bfe_u32 v190, v0, 4, 1
	v_lshl_add_u32 v184, v190, 5, v184
	v_and_b32_e32 v190, 3, v0
	v_lshl_add_u32 v184, v190, 3, v184
	v_add_u32_e32 v184, s30, v184
	v_lshrrev_b32_e32 v187, 3, v0
	v_and_b32_e32 v190, 7, v0
	v_lshlrev_b32_e32 v188, 4, v190
	v_mul_u32_u24_e32 v185, 0x90, v187
	v_add_u32_e32 v185, v185, v188
	v_add_u32_e32 v206, 0xd800, v185
	s_and_b32 s28, s31, 1
	s_lshl_b32 s28, s28, 5
	v_lshlrev_b32_e32 v190, 3, v181
	v_sub_u32_e32 v186, v180, v190
	v_add_u32_e32 v186, s28, v186
	v_mov_b32_e32 v198, 0xff800000
	s_mov_b32 s20, s3
	s_mul_i32 s21, s3, s14
.Lmb_unit:
	s_cmpk_gt_i32 s21, 0x5ff
	s_cbranch_scc1 .Lmb_done
	s_and_b32 s25, s21, 63
	s_lshr_b32 s26, s21, 6
	s_and_b32 s11, s26, 3
	s_lshr_b32 s27, s26, 2
	s_cmp_ge_u32 s27, 3
	s_cselect_b32 s12, 1, 0
	s_mul_i32 s10, s12, 3
	s_sub_i32 s10, s27, s10
	s_lshl_b32 s6, s10, 1
	s_sub_i32 s13, 6, s6
	s_lshr_b32 s7, s25, s13
	s_lshl_b32 s8, 1, s13
	s_add_i32 s8, s8, -1
	s_and_b32 s8, s25, s8
	s_lshl_b32 s8, s8, 8
	s_lshr_b32 s9, 0x4000, s6
	s_add_i32 s15, s9, -1
	s_mul_i32 s28, s12, 0x6000000
	s_add_u32 s4, s94, 0x7800000
	s_addc_u32 s5, s95, 0
	s_add_u32 s4, s4, s28
	s_addc_u32 s5, s5, 0
	s_lshl_b32 s22, s10, 9
	s_lshl_b32 s23, s11, 7
	s_add_i32 s22, s22, s23
	s_add_i32 s22, s22, 0x600
	s_add_i32 s23, s22, 0x600
	s_add_i32 s24, s22, 0xc00
	s_add_u32 s34, s4, s23
	s_addc_u32 s35, s5, 0
	s_add_u32 s36, s4, s24
	s_addc_u32 s37, s5, 0
	s_lshl_b32 s28, s10, 24
	s_lshl_b32 s38, s12, 23
	s_add_i32 s28, s28, s38
	s_lshl_b32 s38, s11, 7
	s_add_i32 s28, s28, s38
	s_add_u32 s16, s94, 0x3800000
	s_addc_u32 s17, s95, 0
	s_add_u32 s16, s16, s28
	s_addc_u32 s17, s17, 0
	s_lshl_b32 s28, s10, 19
	s_lshl_b32 s38, s12, 18
	s_add_i32 s28, s28, s38
	s_lshl_b32 s38, s11, 2
	s_add_i32 s28, s28, s38
	s_add_u32 s18, s94, 0x6800000
	s_addc_u32 s19, s95, 0
	s_add_u32 s18, s18, s28
	s_addc_u32 s19, s19, 0
	s_lshl_b32 s25, s31, 5
	s_add_i32 s25, s25, s8
	v_add_u32_e32 v189, s25, v180
	v_lshlrev_b32_e32 v189, s6, v189
	v_add_u32_e32 v199, s7, v189
	v_mul_u32_u24_e32 v190, 0x1800, v199
	v_lshl_add_u32 v190, v181, 4, v190
	v_add_u32_e32 v190, s22, v190
	global_load_dwordx4 v[100:103], v190, s[4:5]
	global_load_dwordx4 v[104:107], v190, s[4:5] offset:32
	global_load_dwordx4 v[108:111], v190, s[4:5] offset:64
	global_load_dwordx4 v[112:115], v190, s[4:5] offset:96
	s_add_i32 s26, s8, -64
	v_add_u32_e32 v200, s26, v187
	v_med3_i32 v200, v200, 0, s15
	v_lshlrev_b32_e32 v200, s6, v200
	v_add_u32_e32 v200, s7, v200
	v_mul_u32_u24_e32 v200, 0x1800, v200
	v_add_u32_e32 v200, v200, v188
	global_load_dwordx4 v[2:5], v200, s[34:35]
	global_load_dwordx4 v[6:9], v200, s[36:37]
	v_add_u32_e32 v201, s26, v187
	v_add_u32_e32 v201, 64, v201
	v_med3_i32 v201, v201, 0, s15
	v_lshlrev_b32_e32 v201, s6, v201
	v_add_u32_e32 v201, s7, v201
	v_mul_u32_u24_e32 v201, 0x1800, v201
	v_add_u32_e32 v201, v201, v188
	global_load_dwordx4 v[10:13], v201, s[34:35]
	global_load_dwordx4 v[14:17], v201, s[36:37]
	v_add_u32_e32 v202, s26, v187
	v_add_u32_e32 v202, 128, v202
	v_med3_i32 v202, v202, 0, s15
	v_lshlrev_b32_e32 v202, s6, v202
	v_add_u32_e32 v202, s7, v202
	v_mul_u32_u24_e32 v202, 0x1800, v202
	v_add_u32_e32 v202, v202, v188
	global_load_dwordx4 v[18:21], v202, s[34:35]
	global_load_dwordx4 v[22:25], v202, s[36:37]
	v_add_u32_e32 v203, s26, v187
	v_add_u32_e32 v203, 192, v203
	v_med3_i32 v203, v203, 0, s15
	v_lshlrev_b32_e32 v203, s6, v203
	v_add_u32_e32 v203, s7, v203
	v_mul_u32_u24_e32 v203, 0x1800, v203
	v_add_u32_e32 v203, v203, v188
	global_load_dwordx4 v[26:29], v203, s[34:35]
	global_load_dwordx4 v[30:33], v203, s[36:37]
	v_add_u32_e32 v204, s26, v187
	v_add_u32_e32 v204, 256, v204
	v_med3_i32 v204, v204, 0, s15
	v_lshlrev_b32_e32 v204, s6, v204
	v_add_u32_e32 v204, s7, v204
	v_mul_u32_u24_e32 v204, 0x1800, v204
	v_add_u32_e32 v204, v204, v188
	global_load_dwordx4 v[34:37], v204, s[34:35]
	global_load_dwordx4 v[38:41], v204, s[36:37]
	v_add_u32_e32 v205, s26, v187
	v_add_u32_e32 v205, 320, v205
	v_med3_i32 v205, v205, 0, s15
	v_lshlrev_b32_e32 v205, s6, v205
	v_add_u32_e32 v205, s7, v205
	v_mul_u32_u24_e32 v205, 0x1800, v205
	v_add_u32_e32 v205, v205, v188
	global_load_dwordx4 v[42:45], v205, s[34:35]
	global_load_dwordx4 v[46:49], v205, s[36:37]
	s_lshl_b32 s27, s29, 6
	s_add_i32 s27, s27, s26
	s_add_i32 s28, s27, 0
	s_cmp_ge_i32 s28, 0
	s_cselect_b32 s50, 1, 0
	s_cmp_lt_i32 s28, s9
	s_cselect_b32 s50, s50, 0
	s_add_i32 s28, s27, 64
	s_cmp_ge_i32 s28, 0
	s_cselect_b32 s51, 1, 0
	s_cmp_lt_i32 s28, s9
	s_cselect_b32 s51, s51, 0
	s_add_i32 s28, s27, 128
	s_cmp_ge_i32 s28, 0
	s_cselect_b32 s52, 1, 0
	s_cmp_lt_i32 s28, s9
	s_cselect_b32 s52, s52, 0
	s_waitcnt vmcnt(0)
	s_barrier
	ds_write_b128 v185, v[2:5]
	ds_write_b128 v185, v[6:9] offset:9216
	ds_write_b128 v185, v[10:13] offset:18432
	ds_write_b128 v185, v[14:17] offset:27648
	ds_write_b128 v185, v[18:21] offset:36864
	ds_write_b128 v185, v[22:25] offset:46080
	ds_write_b128 v206, v[26:29]
	ds_write_b128 v206, v[30:33] offset:9216
	ds_write_b128 v206, v[34:37] offset:18432
	ds_write_b128 v206, v[38:41] offset:27648
	ds_write_b128 v206, v[42:45] offset:36864
	ds_write_b128 v206, v[46:49] offset:46080
	s_waitcnt lgkmcnt(0)
	s_barrier
	ds_read_b128 v[148:151], v183
	ds_read_b128 v[152:155], v183 offset:32
	ds_read_b128 v[156:159], v183 offset:64
	ds_read_b128 v[160:163], v183 offset:96
	ds_read_b128 v[164:167], v183 offset:4608
	ds_read_b128 v[168:171], v183 offset:4640
	ds_read_b128 v[172:175], v183 offset:4672
	ds_read_b128 v[176:179], v183 offset:4704
	s_waitcnt lgkmcnt(7)
	v_mfma_f32_32x32x16_bf16 v[2:17], v[148:151], v[100:103], 0
	s_waitcnt lgkmcnt(6)
	v_mfma_f32_32x32x16_bf16 v[2:17], v[152:155], v[104:107], v[2:17]
	s_waitcnt lgkmcnt(5)
	v_mfma_f32_32x32x16_bf16 v[2:17], v[156:159], v[108:111], v[2:17]
	s_waitcnt lgkmcnt(4)
	v_mfma_f32_32x32x16_bf16 v[2:17], v[160:163], v[112:115], v[2:17]
	ds_read_b128 v[148:151], v183 offset:18432
	ds_read_b128 v[152:155], v183 offset:18464
	ds_read_b128 v[156:159], v183 offset:18496
	ds_read_b128 v[160:163], v183 offset:18528
	s_waitcnt lgkmcnt(7)
	v_mfma_f32_32x32x16_bf16 v[18:33], v[164:167], v[100:103], 0
	s_waitcnt lgkmcnt(6)
	v_mfma_f32_32x32x16_bf16 v[18:33], v[168:171], v[104:107], v[18:33]
	s_waitcnt lgkmcnt(5)
	v_mfma_f32_32x32x16_bf16 v[18:33], v[172:175], v[108:111], v[18:33]
	s_waitcnt lgkmcnt(4)
	v_mfma_f32_32x32x16_bf16 v[18:33], v[176:179], v[112:115], v[18:33]
	ds_read_b128 v[164:167], v183 offset:23040
	ds_read_b128 v[168:171], v183 offset:23072
	ds_read_b128 v[172:175], v183 offset:23104
	ds_read_b128 v[176:179], v183 offset:23136
	s_waitcnt lgkmcnt(7)
	v_mfma_f32_32x32x16_bf16 v[34:49], v[148:151], v[100:103], 0
	s_waitcnt lgkmcnt(6)
	v_mfma_f32_32x32x16_bf16 v[34:49], v[152:155], v[104:107], v[34:49]
	s_waitcnt lgkmcnt(5)
	v_mfma_f32_32x32x16_bf16 v[34:49], v[156:159], v[108:111], v[34:49]
	s_waitcnt lgkmcnt(4)
	v_mfma_f32_32x32x16_bf16 v[34:49], v[160:163], v[112:115], v[34:49]
	ds_read_b128 v[148:151], v183 offset:36864
	ds_read_b128 v[152:155], v183 offset:36896
	ds_read_b128 v[156:159], v183 offset:36928
	ds_read_b128 v[160:163], v183 offset:36960
	s_waitcnt lgkmcnt(7)
	v_mfma_f32_32x32x16_bf16 v[50:65], v[164:167], v[100:103], 0
	s_waitcnt lgkmcnt(6)
	v_mfma_f32_32x32x16_bf16 v[50:65], v[168:171], v[104:107], v[50:65]
	s_waitcnt lgkmcnt(5)
	v_mfma_f32_32x32x16_bf16 v[50:65], v[172:175], v[108:111], v[50:65]
	s_waitcnt lgkmcnt(4)
	v_mfma_f32_32x32x16_bf16 v[50:65], v[176:179], v[112:115], v[50:65]
	ds_read_b128 v[164:167], v183 offset:41472
	ds_read_b128 v[168:171], v183 offset:41504
	ds_read_b128 v[172:175], v183 offset:41536
	ds_read_b128 v[176:179], v183 offset:41568
	s_waitcnt lgkmcnt(7)
	v_mfma_f32_32x32x16_bf16 v[66:81], v[148:151], v[100:103], 0
	s_waitcnt lgkmcnt(6)
	v_mfma_f32_32x32x16_bf16 v[66:81], v[152:155], v[104:107], v[66:81]
	s_waitcnt lgkmcnt(5)
	v_mfma_f32_32x32x16_bf16 v[66:81], v[156:159], v[108:111], v[66:81]
	s_waitcnt lgkmcnt(4)
	v_mfma_f32_32x32x16_bf16 v[66:81], v[160:163], v[112:115], v[66:81]
	s_waitcnt lgkmcnt(3)
	v_mfma_f32_32x32x16_bf16 v[82:97], v[164:167], v[100:103], 0
	s_waitcnt lgkmcnt(2)
	v_mfma_f32_32x32x16_bf16 v[82:97], v[168:171], v[104:107], v[82:97]
	s_waitcnt lgkmcnt(1)
	v_mfma_f32_32x32x16_bf16 v[82:97], v[172:175], v[108:111], v[82:97]
	s_waitcnt lgkmcnt(0)
	v_mfma_f32_32x32x16_bf16 v[82:97], v[176:179], v[112:115], v[82:97]
	s_cmp_lg_u32 s50, 0
	s_cbranch_scc1 .Lmb_tv0
	s_nop 7
	s_nop 7
	v_mov_b32_e32 v2, v198
	v_mov_b32_e32 v3, v198
	v_mov_b32_e32 v4, v198
	v_mov_b32_e32 v5, v198
	v_mov_b32_e32 v6, v198
	v_mov_b32_e32 v7, v198
	v_mov_b32_e32 v8, v198
	v_mov_b32_e32 v9, v198
	v_mov_b32_e32 v10, v198
	v_mov_b32_e32 v11, v198
	v_mov_b32_e32 v12, v198
	v_mov_b32_e32 v13, v198
	v_mov_b32_e32 v14, v198
	v_mov_b32_e32 v15, v198
	v_mov_b32_e32 v16, v198
	v_mov_b32_e32 v17, v198
	v_mov_b32_e32 v18, v198
	v_mov_b32_e32 v19, v198
	v_mov_b32_e32 v20, v198
	v_mov_b32_e32 v21, v198
	v_mov_b32_e32 v22, v198
	v_mov_b32_e32 v23, v198
	v_mov_b32_e32 v24, v198
	v_mov_b32_e32 v25, v198
	v_mov_b32_e32 v26, v198
	v_mov_b32_e32 v27, v198
	v_mov_b32_e32 v28, v198
	v_mov_b32_e32 v29, v198
	v_mov_b32_e32 v30, v198
	v_mov_b32_e32 v31, v198
	v_mov_b32_e32 v32, v198
	v_mov_b32_e32 v33, v198
.Lmb_tv0:
	s_cmp_lg_u32 s51, 0
	s_cbranch_scc1 .Lmb_tv1
	s_nop 7
	s_nop 7
	v_mov_b32_e32 v34, v198
	v_mov_b32_e32 v35, v198
	v_mov_b32_e32 v36, v198
	v_mov_b32_e32 v37, v198
	v_mov_b32_e32 v38, v198
	v_mov_b32_e32 v39, v198
	v_mov_b32_e32 v40, v198
	v_mov_b32_e32 v41, v198
	v_mov_b32_e32 v42, v198
	v_mov_b32_e32 v43, v198
	v_mov_b32_e32 v44, v198
	v_mov_b32_e32 v45, v198
	v_mov_b32_e32 v46, v198
	v_mov_b32_e32 v47, v198
	v_mov_b32_e32 v48, v198
	v_mov_b32_e32 v49, v198
	v_mov_b32_e32 v50, v198
	v_mov_b32_e32 v51, v198
	v_mov_b32_e32 v52, v198
	v_mov_b32_e32 v53, v198
	v_mov_b32_e32 v54, v198
	v_mov_b32_e32 v55, v198
	v_mov_b32_e32 v56, v198
	v_mov_b32_e32 v57, v198
	v_mov_b32_e32 v58, v198
	v_mov_b32_e32 v59, v198
	v_mov_b32_e32 v60, v198
	v_mov_b32_e32 v61, v198
	v_mov_b32_e32 v62, v198
	v_mov_b32_e32 v63, v198
	v_mov_b32_e32 v64, v198
	v_mov_b32_e32 v65, v198
.Lmb_tv1:
	s_cmp_lg_u32 s52, 0
	s_cbranch_scc1 .Lmb_tv2
	s_nop 7
	s_nop 7
	v_mov_b32_e32 v66, v198
	v_mov_b32_e32 v67, v198
	v_mov_b32_e32 v68, v198
	v_mov_b32_e32 v69, v198
	v_mov_b32_e32 v70, v198
	v_mov_b32_e32 v71, v198
	v_mov_b32_e32 v72, v198
	v_mov_b32_e32 v73, v198
	v_mov_b32_e32 v74, v198
	v_mov_b32_e32 v75, v198
	v_mov_b32_e32 v76, v198
	v_mov_b32_e32 v77, v198
	v_mov_b32_e32 v78, v198
	v_mov_b32_e32 v79, v198
	v_mov_b32_e32 v80, v198
	v_mov_b32_e32 v81, v198
	v_mov_b32_e32 v82, v198
	v_mov_b32_e32 v83, v198
	v_mov_b32_e32 v84, v198
	v_mov_b32_e32 v85, v198
	v_mov_b32_e32 v86, v198
	v_mov_b32_e32 v87, v198
	v_mov_b32_e32 v88, v198
	v_mov_b32_e32 v89, v198
	v_mov_b32_e32 v90, v198
	v_mov_b32_e32 v91, v198
	v_mov_b32_e32 v92, v198
	v_mov_b32_e32 v93, v198
	v_mov_b32_e32 v94, v198
	v_mov_b32_e32 v95, v198
	v_mov_b32_e32 v96, v198
	v_mov_b32_e32 v97, v198
.Lmb_tv2:
	s_nop 7
	s_nop 4
	v_cmp_ge_i32_e64 s[40:41], 0, v186
	v_cmp_ge_i32_e64 s[42:43], 1, v186
	v_cmp_ge_i32_e64 s[44:45], 2, v186
	v_cmp_ge_i32_e64 s[46:47], 3, v186
	v_cndmask_b32_e64 v2, v198, v2, s[40:41]
	v_cndmask_b32_e64 v3, v198, v3, s[42:43]
	v_cndmask_b32_e64 v4, v198, v4, s[44:45]
	v_cndmask_b32_e64 v5, v198, v5, s[46:47]
	v_cmp_ge_i32_e64 s[40:41], 4, v186
	v_cmp_ge_i32_e64 s[42:43], 5, v186
	v_cmp_ge_i32_e64 s[44:45], 6, v186
	v_cmp_ge_i32_e64 s[46:47], 7, v186
	v_cndmask_b32_e64 v6, v198, v6, s[40:41]
	v_cndmask_b32_e64 v7, v198, v7, s[42:43]
	v_cndmask_b32_e64 v8, v198, v8, s[44:45]
	v_cndmask_b32_e64 v9, v198, v9, s[46:47]
	v_cmp_ge_i32_e64 s[40:41], 16, v186
	v_cmp_ge_i32_e64 s[42:43], 17, v186
	v_cmp_ge_i32_e64 s[44:45], 18, v186
	v_cmp_ge_i32_e64 s[46:47], 19, v186
	v_cndmask_b32_e64 v10, v198, v10, s[40:41]
	v_cndmask_b32_e64 v11, v198, v11, s[42:43]
	v_cndmask_b32_e64 v12, v198, v12, s[44:45]
	v_cndmask_b32_e64 v13, v198, v13, s[46:47]
	v_cmp_ge_i32_e64 s[40:41], 20, v186
	v_cmp_ge_i32_e64 s[42:43], 21, v186
	v_cmp_ge_i32_e64 s[44:45], 22, v186
	v_cmp_ge_i32_e64 s[46:47], 23, v186
	v_cndmask_b32_e64 v14, v198, v14, s[40:41]
	v_cndmask_b32_e64 v15, v198, v15, s[42:43]
	v_cndmask_b32_e64 v16, v198, v16, s[44:45]
	v_cndmask_b32_e64 v17, v198, v17, s[46:47]
	v_cmp_ge_i32_e64 s[40:41], 32, v186
	v_cmp_ge_i32_e64 s[42:43], 33, v186
	v_cmp_ge_i32_e64 s[44:45], 34, v186
	v_cmp_ge_i32_e64 s[46:47], 35, v186
	v_cndmask_b32_e64 v18, v198, v18, s[40:41]
	v_cndmask_b32_e64 v19, v198, v19, s[42:43]
	v_cndmask_b32_e64 v20, v198, v20, s[44:45]
	v_cndmask_b32_e64 v21, v198, v21, s[46:47]
	v_cmp_ge_i32_e64 s[40:41], 36, v186
	v_cmp_ge_i32_e64 s[42:43], 37, v186
	v_cmp_ge_i32_e64 s[44:45], 38, v186
	v_cmp_ge_i32_e64 s[46:47], 39, v186
	v_cndmask_b32_e64 v22, v198, v22, s[40:41]
	v_cndmask_b32_e64 v23, v198, v23, s[42:43]
	v_cndmask_b32_e64 v24, v198, v24, s[44:45]
	v_cndmask_b32_e64 v25, v198, v25, s[46:47]
	v_cmp_ge_i32_e64 s[40:41], 48, v186
	v_cmp_ge_i32_e64 s[42:43], 49, v186
	v_cmp_ge_i32_e64 s[44:45], 50, v186
	v_cmp_ge_i32_e64 s[46:47], 51, v186
	v_cndmask_b32_e64 v26, v198, v26, s[40:41]
	v_cndmask_b32_e64 v27, v198, v27, s[42:43]
	v_cndmask_b32_e64 v28, v198, v28, s[44:45]
	v_cndmask_b32_e64 v29, v198, v29, s[46:47]
	v_cmp_ge_i32_e64 s[40:41], 52, v186
	v_cmp_ge_i32_e64 s[42:43], 53, v186
	v_cmp_ge_i32_e64 s[44:45], 54, v186
	v_cmp_ge_i32_e64 s[46:47], 55, v186
	v_cndmask_b32_e64 v30, v198, v30, s[40:41]
	v_cndmask_b32_e64 v31, v198, v31, s[42:43]
	v_cndmask_b32_e64 v32, v198, v32, s[44:45]
	v_cndmask_b32_e64 v33, v198, v33, s[46:47]
	v_cmp_le_i32_e64 s[40:41], 0, v186
	v_cmp_le_i32_e64 s[42:43], 1, v186
	v_cmp_le_i32_e64 s[44:45], 2, v186
	v_cmp_le_i32_e64 s[46:47], 3, v186
	v_cndmask_b32_e64 v66, v198, v66, s[40:41]
	v_cndmask_b32_e64 v67, v198, v67, s[42:43]
	v_cndmask_b32_e64 v68, v198, v68, s[44:45]
	v_cndmask_b32_e64 v69, v198, v69, s[46:47]
	v_cmp_le_i32_e64 s[40:41], 4, v186
	v_cmp_le_i32_e64 s[42:43], 5, v186
	v_cmp_le_i32_e64 s[44:45], 6, v186
	v_cmp_le_i32_e64 s[46:47], 7, v186
	v_cndmask_b32_e64 v70, v198, v70, s[40:41]
	v_cndmask_b32_e64 v71, v198, v71, s[42:43]
	v_cndmask_b32_e64 v72, v198, v72, s[44:45]
	v_cndmask_b32_e64 v73, v198, v73, s[46:47]
	v_cmp_le_i32_e64 s[40:41], 16, v186
	v_cmp_le_i32_e64 s[42:43], 17, v186
	v_cmp_le_i32_e64 s[44:45], 18, v186
	v_cmp_le_i32_e64 s[46:47], 19, v186
	v_cndmask_b32_e64 v74, v198, v74, s[40:41]
	v_cndmask_b32_e64 v75, v198, v75, s[42:43]
	v_cndmask_b32_e64 v76, v198, v76, s[44:45]
	v_cndmask_b32_e64 v77, v198, v77, s[46:47]
	v_cmp_le_i32_e64 s[40:41], 20, v186
	v_cmp_le_i32_e64 s[42:43], 21, v186
	v_cmp_le_i32_e64 s[44:45], 22, v186
	v_cmp_le_i32_e64 s[46:47], 23, v186
	v_cndmask_b32_e64 v78, v198, v78, s[40:41]
	v_cndmask_b32_e64 v79, v198, v79, s[42:43]
	v_cndmask_b32_e64 v80, v198, v80, s[44:45]
	v_cndmask_b32_e64 v81, v198, v81, s[46:47]
	v_cmp_le_i32_e64 s[40:41], 32, v186
	v_cmp_le_i32_e64 s[42:43], 33, v186
	v_cmp_le_i32_e64 s[44:45], 34, v186
	v_cmp_le_i32_e64 s[46:47], 35, v186
	v_cndmask_b32_e64 v82, v198, v82, s[40:41]
	v_cndmask_b32_e64 v83, v198, v83, s[42:43]
	v_cndmask_b32_e64 v84, v198, v84, s[44:45]
	v_cndmask_b32_e64 v85, v198, v85, s[46:47]
	v_cmp_le_i32_e64 s[40:41], 36, v186
	v_cmp_le_i32_e64 s[42:43], 37, v186
	v_cmp_le_i32_e64 s[44:45], 38, v186
	v_cmp_le_i32_e64 s[46:47], 39, v186
	v_cndmask_b32_e64 v86, v198, v86, s[40:41]
	v_cndmask_b32_e64 v87, v198, v87, s[42:43]
	v_cndmask_b32_e64 v88, v198, v88, s[44:45]
	v_cndmask_b32_e64 v89, v198, v89, s[46:47]
	v_cmp_le_i32_e64 s[40:41], 48, v186
	v_cmp_le_i32_e64 s[42:43], 49, v186
	v_cmp_le_i32_e64 s[44:45], 50, v186
	v_cmp_le_i32_e64 s[46:47], 51, v186
	v_cndmask_b32_e64 v90, v198, v90, s[40:41]
	v_cndmask_b32_e64 v91, v198, v91, s[42:43]
	v_cndmask_b32_e64 v92, v198, v92, s[44:45]
	v_cndmask_b32_e64 v93, v198, v93, s[46:47]
	v_cmp_le_i32_e64 s[40:41], 52, v186
	v_cmp_le_i32_e64 s[42:43], 53, v186
	v_cmp_le_i32_e64 s[44:45], 54, v186
	v_cmp_le_i32_e64 s[46:47], 55, v186
	v_cndmask_b32_e64 v94, v198, v94, s[40:41]
	v_cndmask_b32_e64 v95, v198, v95, s[42:43]
	v_cndmask_b32_e64 v96, v198, v96, s[44:45]
	v_cndmask_b32_e64 v97, v198, v97, s[46:47]
	v_max3_f32 v192, v2, v3, v4
	v_max3_f32 v193, v5, v6, v7
	v_max3_f32 v192, v192, v8, v9
	v_max3_f32 v193, v193, v10, v11
	v_max3_f32 v192, v192, v12, v13
	v_max3_f32 v193, v193, v14, v15
	v_max3_f32 v192, v192, v16, v17
	v_max3_f32 v193, v193, v18, v19
	v_max3_f32 v192, v192, v20, v21
	v_max3_f32 v193, v193, v22, v23
	v_max3_f32 v192, v192, v24, v25
	v_max3_f32 v193, v193, v26, v27
	v_max3_f32 v192, v192, v28, v29
	v_max3_f32 v193, v193, v30, v31
	v_max3_f32 v192, v192, v32, v33
	v_max3_f32 v193, v193, v34, v35
	v_max3_f32 v192, v192, v36, v37
	v_max3_f32 v193, v193, v38, v39
	v_max3_f32 v192, v192, v40, v41
	v_max3_f32 v193, v193, v42, v43
	v_max3_f32 v192, v192, v44, v45
	v_max3_f32 v193, v193, v46, v47
	v_max3_f32 v192, v192, v48, v49
	v_max3_f32 v193, v193, v50, v51
	v_max3_f32 v192, v192, v52, v53
	v_max3_f32 v193, v193, v54, v55
	v_max3_f32 v192, v192, v56, v57
	v_max3_f32 v193, v193, v58, v59
	v_max3_f32 v192, v192, v60, v61
	v_max3_f32 v193, v193, v62, v63
	v_max3_f32 v192, v192, v64, v65
	v_max3_f32 v193, v193, v66, v67
	v_max3_f32 v192, v192, v68, v69
	v_max3_f32 v193, v193, v70, v71
	v_max3_f32 v192, v192, v72, v73
	v_max3_f32 v193, v193, v74, v75
	v_max3_f32 v192, v192, v76, v77
	v_max3_f32 v193, v193, v78, v79
	v_max3_f32 v192, v192, v80, v81
	v_max3_f32 v193, v193, v82, v83
	v_max3_f32 v192, v192, v84, v85
	v_max3_f32 v193, v193, v86, v87
	v_max3_f32 v192, v192, v88, v89
	v_max3_f32 v193, v193, v90, v91
	v_max3_f32 v192, v192, v92, v93
	v_max3_f32 v193, v193, v94, v95
	v_max3_f32 v192, v192, v96, v97
	v_max_f32_e32 v192, v192, v193
	v_mov_b32_e32 v193, v192
	s_nop 1
	v_permlane32_swap_b32_e32 v192, v193
	v_max_f32_e32 v192, v192, v193
	v_mov_b32_e32 v194, 0
	v_mov_b32_e32 v195, 0
	v_mov_b32_e32 v196, 0
	v_mov_b32_e32 v197, 0
	v_sub_f32_e32 v2, v2, v192
	v_sub_f32_e32 v3, v3, v192
	v_exp_f32_e32 v2, v2
	v_exp_f32_e32 v3, v3
	v_add_f32_e32 v194, v194, v2
	v_add_f32_e32 v195, v195, v3
	v_cvt_pk_bf16_f32 v2, v2, v3
	v_sub_f32_e32 v4, v4, v192
	v_sub_f32_e32 v5, v5, v192
	v_exp_f32_e32 v4, v4
	v_exp_f32_e32 v5, v5
	v_add_f32_e32 v196, v196, v4
	v_add_f32_e32 v197, v197, v5
	v_cvt_pk_bf16_f32 v3, v4, v5
	v_sub_f32_e32 v6, v6, v192
	v_sub_f32_e32 v7, v7, v192
	v_exp_f32_e32 v6, v6
	v_exp_f32_e32 v7, v7
	v_add_f32_e32 v194, v194, v6
	v_add_f32_e32 v195, v195, v7
	v_cvt_pk_bf16_f32 v4, v6, v7
	v_sub_f32_e32 v8, v8, v192
	v_sub_f32_e32 v9, v9, v192
	v_exp_f32_e32 v8, v8
	v_exp_f32_e32 v9, v9
	v_add_f32_e32 v196, v196, v8
	v_add_f32_e32 v197, v197, v9
	v_cvt_pk_bf16_f32 v5, v8, v9
	v_sub_f32_e32 v10, v10, v192
	v_sub_f32_e32 v11, v11, v192
	v_exp_f32_e32 v10, v10
	v_exp_f32_e32 v11, v11
	v_add_f32_e32 v194, v194, v10
	v_add_f32_e32 v195, v195, v11
	v_cvt_pk_bf16_f32 v10, v10, v11
	v_sub_f32_e32 v12, v12, v192
	v_sub_f32_e32 v13, v13, v192
	v_exp_f32_e32 v12, v12
	v_exp_f32_e32 v13, v13
	v_add_f32_e32 v196, v196, v12
	v_add_f32_e32 v197, v197, v13
	v_cvt_pk_bf16_f32 v11, v12, v13
	v_sub_f32_e32 v14, v14, v192
	v_sub_f32_e32 v15, v15, v192
	v_exp_f32_e32 v14, v14
	v_exp_f32_e32 v15, v15
	v_add_f32_e32 v194, v194, v14
	v_add_f32_e32 v195, v195, v15
	v_cvt_pk_bf16_f32 v12, v14, v15
	v_sub_f32_e32 v16, v16, v192
	v_sub_f32_e32 v17, v17, v192
	v_exp_f32_e32 v16, v16
	v_exp_f32_e32 v17, v17
	v_add_f32_e32 v196, v196, v16
	v_add_f32_e32 v197, v197, v17
	v_cvt_pk_bf16_f32 v13, v16, v17
	v_sub_f32_e32 v18, v18, v192
	v_sub_f32_e32 v19, v19, v192
	v_exp_f32_e32 v18, v18
	v_exp_f32_e32 v19, v19
	v_add_f32_e32 v194, v194, v18
	v_add_f32_e32 v195, v195, v19
	v_cvt_pk_bf16_f32 v18, v18, v19
	v_sub_f32_e32 v20, v20, v192
	v_sub_f32_e32 v21, v21, v192
	v_exp_f32_e32 v20, v20
	v_exp_f32_e32 v21, v21
	v_add_f32_e32 v196, v196, v20
	v_add_f32_e32 v197, v197, v21
	v_cvt_pk_bf16_f32 v19, v20, v21
	v_sub_f32_e32 v22, v22, v192
	v_sub_f32_e32 v23, v23, v192
	v_exp_f32_e32 v22, v22
	v_exp_f32_e32 v23, v23
	v_add_f32_e32 v194, v194, v22
	v_add_f32_e32 v195, v195, v23
	v_cvt_pk_bf16_f32 v20, v22, v23
	v_sub_f32_e32 v24, v24, v192
	v_sub_f32_e32 v25, v25, v192
	v_exp_f32_e32 v24, v24
	v_exp_f32_e32 v25, v25
	v_add_f32_e32 v196, v196, v24
	v_add_f32_e32 v197, v197, v25
	v_cvt_pk_bf16_f32 v21, v24, v25
	v_sub_f32_e32 v26, v26, v192
	v_sub_f32_e32 v27, v27, v192
	v_exp_f32_e32 v26, v26
	v_exp_f32_e32 v27, v27
	v_add_f32_e32 v194, v194, v26
	v_add_f32_e32 v195, v195, v27
	v_cvt_pk_bf16_f32 v26, v26, v27
	v_sub_f32_e32 v28, v28, v192
	v_sub_f32_e32 v29, v29, v192
	v_exp_f32_e32 v28, v28
	v_exp_f32_e32 v29, v29
	v_add_f32_e32 v196, v196, v28
	v_add_f32_e32 v197, v197, v29
	v_cvt_pk_bf16_f32 v27, v28, v29
	v_sub_f32_e32 v30, v30, v192
	v_sub_f32_e32 v31, v31, v192
	v_exp_f32_e32 v30, v30
	v_exp_f32_e32 v31, v31
	v_add_f32_e32 v194, v194, v30
	v_add_f32_e32 v195, v195, v31
	v_cvt_pk_bf16_f32 v28, v30, v31
	v_sub_f32_e32 v32, v32, v192
	v_sub_f32_e32 v33, v33, v192
	v_exp_f32_e32 v32, v32
	v_exp_f32_e32 v33, v33
	v_add_f32_e32 v196, v196, v32
	v_add_f32_e32 v197, v197, v33
	v_cvt_pk_bf16_f32 v29, v32, v33
	v_sub_f32_e32 v34, v34, v192
	v_sub_f32_e32 v35, v35, v192
	v_exp_f32_e32 v34, v34
	v_exp_f32_e32 v35, v35
	v_add_f32_e32 v194, v194, v34
	v_add_f32_e32 v195, v195, v35
	v_cvt_pk_bf16_f32 v34, v34, v35
	v_sub_f32_e32 v36, v36, v192
	v_sub_f32_e32 v37, v37, v192
	v_exp_f32_e32 v36, v36
	v_exp_f32_e32 v37, v37
	v_add_f32_e32 v196, v196, v36
	v_add_f32_e32 v197, v197, v37
	v_cvt_pk_bf16_f32 v35, v36, v37
	v_sub_f32_e32 v38, v38, v192
	v_sub_f32_e32 v39, v39, v192
	v_exp_f32_e32 v38, v38
	v_exp_f32_e32 v39, v39
	v_add_f32_e32 v194, v194, v38
	v_add_f32_e32 v195, v195, v39
	v_cvt_pk_bf16_f32 v36, v38, v39
	v_sub_f32_e32 v40, v40, v192
	v_sub_f32_e32 v41, v41, v192
	v_exp_f32_e32 v40, v40
	v_exp_f32_e32 v41, v41
	v_add_f32_e32 v196, v196, v40
	v_add_f32_e32 v197, v197, v41
	v_cvt_pk_bf16_f32 v37, v40, v41
	v_sub_f32_e32 v42, v42, v192
	v_sub_f32_e32 v43, v43, v192
	v_exp_f32_e32 v42, v42
	v_exp_f32_e32 v43, v43
	v_add_f32_e32 v194, v194, v42
	v_add_f32_e32 v195, v195, v43
	v_cvt_pk_bf16_f32 v42, v42, v43
	v_sub_f32_e32 v44, v44, v192
	v_sub_f32_e32 v45, v45, v192
	v_exp_f32_e32 v44, v44
	v_exp_f32_e32 v45, v45
	v_add_f32_e32 v196, v196, v44
	v_add_f32_e32 v197, v197, v45
	v_cvt_pk_bf16_f32 v43, v44, v45
	v_sub_f32_e32 v46, v46, v192
	v_sub_f32_e32 v47, v47, v192
	v_exp_f32_e32 v46, v46
	v_exp_f32_e32 v47, v47
	v_add_f32_e32 v194, v194, v46
	v_add_f32_e32 v195, v195, v47
	v_cvt_pk_bf16_f32 v44, v46, v47
	v_sub_f32_e32 v48, v48, v192
	v_sub_f32_e32 v49, v49, v192
	v_exp_f32_e32 v48, v48
	v_exp_f32_e32 v49, v49
	v_add_f32_e32 v196, v196, v48
	v_add_f32_e32 v197, v197, v49
	v_cvt_pk_bf16_f32 v45, v48, v49
	v_sub_f32_e32 v50, v50, v192
	v_sub_f32_e32 v51, v51, v192
	v_exp_f32_e32 v50, v50
	v_exp_f32_e32 v51, v51
	v_add_f32_e32 v194, v194, v50
	v_add_f32_e32 v195, v195, v51
	v_cvt_pk_bf16_f32 v50, v50, v51
	v_sub_f32_e32 v52, v52, v192
	v_sub_f32_e32 v53, v53, v192
	v_exp_f32_e32 v52, v52
	v_exp_f32_e32 v53, v53
	v_add_f32_e32 v196, v196, v52
	v_add_f32_e32 v197, v197, v53
	v_cvt_pk_bf16_f32 v51, v52, v53
	v_sub_f32_e32 v54, v54, v192
	v_sub_f32_e32 v55, v55, v192
	v_exp_f32_e32 v54, v54
	v_exp_f32_e32 v55, v55
	v_add_f32_e32 v194, v194, v54
	v_add_f32_e32 v195, v195, v55
	v_cvt_pk_bf16_f32 v52, v54, v55
	v_sub_f32_e32 v56, v56, v192
	v_sub_f32_e32 v57, v57, v192
	v_exp_f32_e32 v56, v56
	v_exp_f32_e32 v57, v57
	v_add_f32_e32 v196, v196, v56
	v_add_f32_e32 v197, v197, v57
	v_cvt_pk_bf16_f32 v53, v56, v57
	v_sub_f32_e32 v58, v58, v192
	v_sub_f32_e32 v59, v59, v192
	v_exp_f32_e32 v58, v58
	v_exp_f32_e32 v59, v59
	v_add_f32_e32 v194, v194, v58
	v_add_f32_e32 v195, v195, v59
	v_cvt_pk_bf16_f32 v58, v58, v59
	v_sub_f32_e32 v60, v60, v192
	v_sub_f32_e32 v61, v61, v192
	v_exp_f32_e32 v60, v60
	v_exp_f32_e32 v61, v61
	v_add_f32_e32 v196, v196, v60
	v_add_f32_e32 v197, v197, v61
	v_cvt_pk_bf16_f32 v59, v60, v61
	v_sub_f32_e32 v62, v62, v192
	v_sub_f32_e32 v63, v63, v192
	v_exp_f32_e32 v62, v62
	v_exp_f32_e32 v63, v63
	v_add_f32_e32 v194, v194, v62
	v_add_f32_e32 v195, v195, v63
	v_cvt_pk_bf16_f32 v60, v62, v63
	v_sub_f32_e32 v64, v64, v192
	v_sub_f32_e32 v65, v65, v192
	v_exp_f32_e32 v64, v64
	v_exp_f32_e32 v65, v65
	v_add_f32_e32 v196, v196, v64
	v_add_f32_e32 v197, v197, v65
	v_cvt_pk_bf16_f32 v61, v64, v65
	v_sub_f32_e32 v66, v66, v192
	v_sub_f32_e32 v67, v67, v192
	v_exp_f32_e32 v66, v66
	v_exp_f32_e32 v67, v67
	v_add_f32_e32 v194, v194, v66
	v_add_f32_e32 v195, v195, v67
	v_cvt_pk_bf16_f32 v66, v66, v67
	v_sub_f32_e32 v68, v68, v192
	v_sub_f32_e32 v69, v69, v192
	v_exp_f32_e32 v68, v68
	v_exp_f32_e32 v69, v69
	v_add_f32_e32 v196, v196, v68
	v_add_f32_e32 v197, v197, v69
	v_cvt_pk_bf16_f32 v67, v68, v69
	v_sub_f32_e32 v70, v70, v192
	v_sub_f32_e32 v71, v71, v192
	v_exp_f32_e32 v70, v70
	v_exp_f32_e32 v71, v71
	v_add_f32_e32 v194, v194, v70
	v_add_f32_e32 v195, v195, v71
	v_cvt_pk_bf16_f32 v68, v70, v71
	v_sub_f32_e32 v72, v72, v192
	v_sub_f32_e32 v73, v73, v192
	v_exp_f32_e32 v72, v72
	v_exp_f32_e32 v73, v73
	v_add_f32_e32 v196, v196, v72
	v_add_f32_e32 v197, v197, v73
	v_cvt_pk_bf16_f32 v69, v72, v73
	v_sub_f32_e32 v74, v74, v192
	v_sub_f32_e32 v75, v75, v192
	v_exp_f32_e32 v74, v74
	v_exp_f32_e32 v75, v75
	v_add_f32_e32 v194, v194, v74
	v_add_f32_e32 v195, v195, v75
	v_cvt_pk_bf16_f32 v74, v74, v75
	v_sub_f32_e32 v76, v76, v192
	v_sub_f32_e32 v77, v77, v192
	v_exp_f32_e32 v76, v76
	v_exp_f32_e32 v77, v77
	v_add_f32_e32 v196, v196, v76
	v_add_f32_e32 v197, v197, v77
	v_cvt_pk_bf16_f32 v75, v76, v77
	v_sub_f32_e32 v78, v78, v192
	v_sub_f32_e32 v79, v79, v192
	v_exp_f32_e32 v78, v78
	v_exp_f32_e32 v79, v79
	v_add_f32_e32 v194, v194, v78
	v_add_f32_e32 v195, v195, v79
	v_cvt_pk_bf16_f32 v76, v78, v79
	v_sub_f32_e32 v80, v80, v192
	v_sub_f32_e32 v81, v81, v192
	v_exp_f32_e32 v80, v80
	v_exp_f32_e32 v81, v81
	v_add_f32_e32 v196, v196, v80
	v_add_f32_e32 v197, v197, v81
	v_cvt_pk_bf16_f32 v77, v80, v81
	v_sub_f32_e32 v82, v82, v192
	v_sub_f32_e32 v83, v83, v192
	v_exp_f32_e32 v82, v82
	v_exp_f32_e32 v83, v83
	v_add_f32_e32 v194, v194, v82
	v_add_f32_e32 v195, v195, v83
	v_cvt_pk_bf16_f32 v82, v82, v83
	v_sub_f32_e32 v84, v84, v192
	v_sub_f32_e32 v85, v85, v192
	v_exp_f32_e32 v84, v84
	v_exp_f32_e32 v85, v85
	v_add_f32_e32 v196, v196, v84
	v_add_f32_e32 v197, v197, v85
	v_cvt_pk_bf16_f32 v83, v84, v85
	v_sub_f32_e32 v86, v86, v192
	v_sub_f32_e32 v87, v87, v192
	v_exp_f32_e32 v86, v86
	v_exp_f32_e32 v87, v87
	v_add_f32_e32 v194, v194, v86
	v_add_f32_e32 v195, v195, v87
	v_cvt_pk_bf16_f32 v84, v86, v87
	v_sub_f32_e32 v88, v88, v192
	v_sub_f32_e32 v89, v89, v192
	v_exp_f32_e32 v88, v88
	v_exp_f32_e32 v89, v89
	v_add_f32_e32 v196, v196, v88
	v_add_f32_e32 v197, v197, v89
	v_cvt_pk_bf16_f32 v85, v88, v89
	v_sub_f32_e32 v90, v90, v192
	v_sub_f32_e32 v91, v91, v192
	v_exp_f32_e32 v90, v90
	v_exp_f32_e32 v91, v91
	v_add_f32_e32 v194, v194, v90
	v_add_f32_e32 v195, v195, v91
	v_cvt_pk_bf16_f32 v90, v90, v91
	v_sub_f32_e32 v92, v92, v192
	v_sub_f32_e32 v93, v93, v192
	v_exp_f32_e32 v92, v92
	v_exp_f32_e32 v93, v93
	v_add_f32_e32 v196, v196, v92
	v_add_f32_e32 v197, v197, v93
	v_cvt_pk_bf16_f32 v91, v92, v93
	v_sub_f32_e32 v94, v94, v192
	v_sub_f32_e32 v95, v95, v192
	v_exp_f32_e32 v94, v94
	v_exp_f32_e32 v95, v95
	v_add_f32_e32 v194, v194, v94
	v_add_f32_e32 v195, v195, v95
	v_cvt_pk_bf16_f32 v92, v94, v95
	v_sub_f32_e32 v96, v96, v192
	v_sub_f32_e32 v97, v97, v192
	v_exp_f32_e32 v96, v96
	v_exp_f32_e32 v97, v97
	v_add_f32_e32 v196, v196, v96
	v_add_f32_e32 v197, v197, v97
	v_cvt_pk_bf16_f32 v93, v96, v97
	ds_read_b64_tr_b16 v[148:149], v184 offset:9216
	ds_read_b64_tr_b16 v[150:151], v184 offset:9792
	ds_read_b64_tr_b16 v[152:153], v184 offset:9280
	ds_read_b64_tr_b16 v[154:155], v184 offset:9856
	ds_read_b64_tr_b16 v[156:157], v184 offset:11520
	ds_read_b64_tr_b16 v[158:159], v184 offset:12096
	ds_read_b64_tr_b16 v[160:161], v184 offset:11584
	ds_read_b64_tr_b16 v[162:163], v184 offset:12160
	ds_read_b64_tr_b16 v[164:165], v184 offset:13824
	ds_read_b64_tr_b16 v[166:167], v184 offset:14400
	ds_read_b64_tr_b16 v[168:169], v184 offset:13888
	ds_read_b64_tr_b16 v[170:171], v184 offset:14464
	s_waitcnt lgkmcnt(10)
	v_mfma_f32_32x32x16_bf16 v[116:131], v[148:151], v[2:5], 0
	s_waitcnt lgkmcnt(8)
	v_mfma_f32_32x32x16_bf16 v[132:147], v[152:155], v[2:5], 0
	ds_read_b64_tr_b16 v[172:173], v184 offset:16128
	ds_read_b64_tr_b16 v[174:175], v184 offset:16704
	ds_read_b64_tr_b16 v[176:177], v184 offset:16192
	ds_read_b64_tr_b16 v[178:179], v184 offset:16768
	s_waitcnt lgkmcnt(10)
	v_mfma_f32_32x32x16_bf16 v[116:131], v[156:159], v[10:13], v[116:131]
	s_waitcnt lgkmcnt(8)
	v_mfma_f32_32x32x16_bf16 v[132:147], v[160:163], v[10:13], v[132:147]
	ds_read_b64_tr_b16 v[148:149], v184 offset:27648
	ds_read_b64_tr_b16 v[150:151], v184 offset:28224
	ds_read_b64_tr_b16 v[152:153], v184 offset:27712
	ds_read_b64_tr_b16 v[154:155], v184 offset:28288
	s_waitcnt lgkmcnt(10)
	v_mfma_f32_32x32x16_bf16 v[116:131], v[164:167], v[18:21], v[116:131]
	s_waitcnt lgkmcnt(8)
	v_mfma_f32_32x32x16_bf16 v[132:147], v[168:171], v[18:21], v[132:147]
	ds_read_b64_tr_b16 v[156:157], v184 offset:29952
	ds_read_b64_tr_b16 v[158:159], v184 offset:30528
	ds_read_b64_tr_b16 v[160:161], v184 offset:30016
	ds_read_b64_tr_b16 v[162:163], v184 offset:30592
	s_waitcnt lgkmcnt(10)
	v_mfma_f32_32x32x16_bf16 v[116:131], v[172:175], v[26:29], v[116:131]
	s_waitcnt lgkmcnt(8)
	v_mfma_f32_32x32x16_bf16 v[132:147], v[176:179], v[26:29], v[132:147]
	ds_read_b64_tr_b16 v[164:165], v184 offset:32256
	ds_read_b64_tr_b16 v[166:167], v184 offset:32832
	ds_read_b64_tr_b16 v[168:169], v184 offset:32320
	ds_read_b64_tr_b16 v[170:171], v184 offset:32896
	s_waitcnt lgkmcnt(10)
	v_mfma_f32_32x32x16_bf16 v[116:131], v[148:151], v[34:37], v[116:131]
	s_waitcnt lgkmcnt(8)
	v_mfma_f32_32x32x16_bf16 v[132:147], v[152:155], v[34:37], v[132:147]
	ds_read_b64_tr_b16 v[172:173], v184 offset:34560
	ds_read_b64_tr_b16 v[174:175], v184 offset:35136
	ds_read_b64_tr_b16 v[176:177], v184 offset:34624
	ds_read_b64_tr_b16 v[178:179], v184 offset:35200
	s_waitcnt lgkmcnt(10)
	v_mfma_f32_32x32x16_bf16 v[116:131], v[156:159], v[42:45], v[116:131]
	s_waitcnt lgkmcnt(8)
	v_mfma_f32_32x32x16_bf16 v[132:147], v[160:163], v[42:45], v[132:147]
	ds_read_b64_tr_b16 v[148:149], v184 offset:46080
	ds_read_b64_tr_b16 v[150:151], v184 offset:46656
	ds_read_b64_tr_b16 v[152:153], v184 offset:46144
	ds_read_b64_tr_b16 v[154:155], v184 offset:46720
	s_waitcnt lgkmcnt(10)
	v_mfma_f32_32x32x16_bf16 v[116:131], v[164:167], v[50:53], v[116:131]
	s_waitcnt lgkmcnt(8)
	v_mfma_f32_32x32x16_bf16 v[132:147], v[168:171], v[50:53], v[132:147]
	ds_read_b64_tr_b16 v[156:157], v184 offset:48384
	ds_read_b64_tr_b16 v[158:159], v184 offset:48960
	ds_read_b64_tr_b16 v[160:161], v184 offset:48448
	ds_read_b64_tr_b16 v[162:163], v184 offset:49024
	s_waitcnt lgkmcnt(10)
	v_mfma_f32_32x32x16_bf16 v[116:131], v[172:175], v[58:61], v[116:131]
	s_waitcnt lgkmcnt(8)
	v_mfma_f32_32x32x16_bf16 v[132:147], v[176:179], v[58:61], v[132:147]
	ds_read_b64_tr_b16 v[164:165], v184 offset:50688
	ds_read_b64_tr_b16 v[166:167], v184 offset:51264
	ds_read_b64_tr_b16 v[168:169], v184 offset:50752
	ds_read_b64_tr_b16 v[170:171], v184 offset:51328
	s_waitcnt lgkmcnt(10)
	v_mfma_f32_32x32x16_bf16 v[116:131], v[148:151], v[66:69], v[116:131]
	s_waitcnt lgkmcnt(8)
	v_mfma_f32_32x32x16_bf16 v[132:147], v[152:155], v[66:69], v[132:147]
	ds_read_b64_tr_b16 v[172:173], v184 offset:52992
	ds_read_b64_tr_b16 v[174:175], v184 offset:53568
	ds_read_b64_tr_b16 v[176:177], v184 offset:53056
	ds_read_b64_tr_b16 v[178:179], v184 offset:53632
	s_waitcnt lgkmcnt(10)
	v_mfma_f32_32x32x16_bf16 v[116:131], v[156:159], v[74:77], v[116:131]
	s_waitcnt lgkmcnt(8)
	v_mfma_f32_32x32x16_bf16 v[132:147], v[160:163], v[74:77], v[132:147]
	s_waitcnt lgkmcnt(6)
	v_mfma_f32_32x32x16_bf16 v[116:131], v[164:167], v[82:85], v[116:131]
	s_waitcnt lgkmcnt(4)
	v_mfma_f32_32x32x16_bf16 v[132:147], v[168:171], v[82:85], v[132:147]
	s_waitcnt lgkmcnt(2)
	v_mfma_f32_32x32x16_bf16 v[116:131], v[172:175], v[90:93], v[116:131]
	s_waitcnt lgkmcnt(0)
	v_mfma_f32_32x32x16_bf16 v[132:147], v[176:179], v[90:93], v[132:147]
	v_add_f32_e32 v194, v194, v195
	v_add_f32_e32 v196, v196, v197
	v_add_f32_e32 v194, v194, v196
	v_mov_b32_e32 v195, v194
	s_nop 1
	v_permlane32_swap_b32_e32 v194, v195
	v_add_f32_e32 v194, v194, v195
	v_rcp_f32_e32 v195, v194
	v_log_f32_e32 v196, v194
	v_fma_f32 v197, -v194, v195, 2.0
	v_mul_f32_e32 v195, v195, v197
	v_add_f32_e32 v196, v192, v196
	v_mul_f32_e32 v116, v116, v195
	v_mul_f32_e32 v117, v117, v195
	v_mul_f32_e32 v118, v118, v195
	v_mul_f32_e32 v119, v119, v195
	v_mul_f32_e32 v120, v120, v195
	v_mul_f32_e32 v121, v121, v195
	v_mul_f32_e32 v122, v122, v195
	v_mul_f32_e32 v123, v123, v195
	v_mul_f32_e32 v124, v124, v195
	v_mul_f32_e32 v125, v125, v195
	v_mul_f32_e32 v126, v126, v195
	v_mul_f32_e32 v127, v127, v195
	v_mul_f32_e32 v128, v128, v195
	v_mul_f32_e32 v129, v129, v195
	v_mul_f32_e32 v130, v130, v195
	v_mul_f32_e32 v131, v131, v195
	v_mul_f32_e32 v132, v132, v195
	v_mul_f32_e32 v133, v133, v195
	v_mul_f32_e32 v134, v134, v195
	v_mul_f32_e32 v135, v135, v195
	v_mul_f32_e32 v136, v136, v195
	v_mul_f32_e32 v137, v137, v195
	v_mul_f32_e32 v138, v138, v195
	v_mul_f32_e32 v139, v139, v195
	v_mul_f32_e32 v140, v140, v195
	v_mul_f32_e32 v141, v141, v195
	v_mul_f32_e32 v142, v142, v195
	v_mul_f32_e32 v143, v143, v195
	v_mul_f32_e32 v144, v144, v195
	v_mul_f32_e32 v145, v145, v195
	v_mul_f32_e32 v146, v146, v195
	v_mul_f32_e32 v147, v147, v195
	v_lshlrev_b32_e32 v189, 9, v199
	v_lshl_add_u32 v189, v181, 4, v189
	v_cvt_pk_bf16_f32 v208, v116, v117
	v_cvt_pk_bf16_f32 v209, v118, v119
	v_cvt_pk_bf16_f32 v210, v120, v121
	v_cvt_pk_bf16_f32 v211, v122, v123
	s_nop 1
	v_permlane32_swap_b32_e32 v208, v210
	v_permlane32_swap_b32_e32 v209, v211
	global_store_dwordx4 v189, v[208:211], s[16:17] offset:0
	v_cvt_pk_bf16_f32 v212, v124, v125
	v_cvt_pk_bf16_f32 v213, v126, v127
	v_cvt_pk_bf16_f32 v214, v128, v129
	v_cvt_pk_bf16_f32 v215, v130, v131
	s_nop 1
	v_permlane32_swap_b32_e32 v212, v214
	v_permlane32_swap_b32_e32 v213, v215
	global_store_dwordx4 v189, v[212:215], s[16:17] offset:32
	v_cvt_pk_bf16_f32 v208, v132, v133
	v_cvt_pk_bf16_f32 v209, v134, v135
	v_cvt_pk_bf16_f32 v210, v136, v137
	v_cvt_pk_bf16_f32 v211, v138, v139
	s_nop 1
	v_permlane32_swap_b32_e32 v208, v210
	v_permlane32_swap_b32_e32 v209, v211
	global_store_dwordx4 v189, v[208:211], s[16:17] offset:64
	v_cvt_pk_bf16_f32 v212, v140, v141
	v_cvt_pk_bf16_f32 v213, v142, v143
	v_cvt_pk_bf16_f32 v214, v144, v145
	v_cvt_pk_bf16_f32 v215, v146, v147
	s_nop 1
	v_permlane32_swap_b32_e32 v212, v214
	v_permlane32_swap_b32_e32 v213, v215
	global_store_dwordx4 v189, v[212:215], s[16:17] offset:96
	v_lshlrev_b32_e32 v190, 4, v199
	v_cmp_eq_u32_e32 vcc, 0, v181
	s_nop 1
	s_and_saveexec_b64 s[38:39], vcc
	global_store_dword v190, v196, s[18:19]
	s_mov_b64 exec, s[38:39]
	s_add_i32 s21, s21, 1
	s_add_i32 s20, s20, -1
	s_cmp_lg_u32 s20, 0
	s_cbranch_scc1 .Lmb_unit
.Lmb_done:
.LBB0_392:
	s_cmp_lt_i32 s73, 6
	s_cbranch_scc1 .LBB0_442
	s_waitcnt vmcnt(0)
	v_cmp_eq_u32_e32 vcc, 0, v0
	s_waitcnt lgkmcnt(0)
	s_barrier
	s_and_saveexec_b64 s[0:1], vcc
	s_cbranch_execz .LBB0_441
	s_add_i32 s3, 0, 0x21000
	v_mov_b32_e32 v1, s3
	s_waitcnt vmcnt(0) expcnt(0) lgkmcnt(0)
	ds_read_b32 v3, v1
	s_add_i32 s3, 0, 0x21004
	v_mov_b32_e32 v1, s3
	ds_read_b32 v1, v1
	s_waitcnt lgkmcnt(1)
	v_cmp_ne_u32_e32 vcc, 0, v3
	s_cbranch_vccnz .LBB0_409
	s_add_u32 s4, s94, 0x40200
	s_addc_u32 s5, s95, 0
	s_add_u32 s6, s94, 0x40400
	s_addc_u32 s7, s95, 0
	s_add_u32 s8, s94, 0x40500
	s_addc_u32 s9, s95, 0
	s_add_u32 s10, s94, 0x40600
	s_addc_u32 s11, s95, 0
	s_add_u32 s12, s94, 0x40700
	s_addc_u32 s13, s95, 0
	s_add_u32 s14, s94, 0x40800
	s_addc_u32 s15, s95, 0
	s_add_u32 s16, s94, 0x40900
	s_addc_u32 s17, s95, 0
	s_add_u32 s18, s94, 0x40a00
	s_addc_u32 s19, s95, 0
	s_add_u32 s20, s94, 0x40b00
	s_addc_u32 s21, s95, 0
	s_add_u32 s22, s94, 0x40c00
	s_addc_u32 s23, s95, 0
	s_add_u32 s24, s94, 0x40d00
	s_addc_u32 s25, s95, 0
	s_add_u32 s26, s94, 0x40e00
	s_addc_u32 s27, s95, 0
	s_add_u32 s28, s94, 0x40f00
	s_addc_u32 s29, s95, 0
	s_add_u32 s30, s94, 0x41000
	s_addc_u32 s31, s95, 0
	s_add_u32 s34, s94, 0x41100
	s_addc_u32 s35, s95, 0
	s_add_u32 s36, s94, 0x41200
	v_readlane_b32 s3, v233, 0
	s_addc_u32 s37, s95, 0
	s_mul_i32 s3, s75, s3
	s_add_u32 s38, s94, 0x41300
	s_mul_i32 s3, s3, s74
	s_addc_u32 s39, s95, 0
	s_mov_b32 s33, 1
	v_mov_b32_e32 v17, 0
	s_branch .LBB0_397
